# pa_first_k_iteration_peeled_c0
# speedup vs baseline: 1.0163x; 1.0039x over previous
; #define PG8_STAGE(bufoff, gbase, voff) do { _Pragma("unroll") for (int _i = 0; _i < 2; ++_i) \
;         __builtin_amdgcn_global_load_lds((const unsigned*)((const char*)(gbase) + (voff)[_i]), (LAS unsigned*)(lds + (bufoff) + ldsw + _i * 8192), 16, 0, 0); } while (0)
; #define PG8_LDA(dst, b, h) do { _Pragma("unroll") for (int m = 0; m < 4; ++m) _Pragma("unroll") for (int k = 0; k < 2; ++k) dst[m][k] = *(const LAS bf16x8*)(lds + PG8_SA(b, h) + aoff + m * 2048 + k * 1024); } while (0)
; #define PG8_LDB(dst, b, h) do { _Pragma("unroll") for (int n = 0; n < 2; ++n) _Pragma("unroll") for (int k = 0; k < 2; ++k) dst[n][k] = *(const LAS bf16x8*)(lds + PG8_SB(b, h) + boff + n * 2048 + k * 1024); } while (0)
; #define PG8_MMA(ai, bj, At, Bt) do { __builtin_amdgcn_s_setprio(1); _Pragma("unroll") for (int m = 0; m < 4; ++m) _Pragma("unroll") for (int n = 0; n < 2; ++n) _Pragma("unroll") for (int k = 0; k < 2; ++k) \
;         acc[ai][bj][m][n] = __builtin_amdgcn_mfma_f32_16x16x32_bf16(Bt[n][k], At[m][k], acc[ai][bj][m][n], 0, 0, 0); __builtin_amdgcn_s_setprio(0); } while (0)
; #define PG8_WAIT_V(n) asm volatile("s_waitcnt vmcnt(" #n ")" ::: "memory")
; #define PG8_WAIT_L(n) asm volatile("s_waitcnt lgkmcnt(" #n ")" ::: "memory")
; #define PG8_BAR __builtin_amdgcn_s_barrier()
; #define PG8_SCHED __builtin_amdgcn_sched_barrier(0)
; template <class Epi, class Sched>
; __device__ __forceinline__ void gemm_phase(LAS unsigned char* lds, const Sched& S, const Epi& E, bool natural = false) {
;     ...
;             PG8_LDB(B0, 0, 0); PG8_LDB(B1, 0, 1); PG8_SCHED; PG8_LDA(At, 0, 0); PG8_STAGE(PG8_SA(1, 1), a1 + hstep, voffA);
;             PG8_WAIT_V(8); PG8_WAIT_L(0); PG8_BAR; PG8_MMA(0, 0, At, B0); PG8_MMA(0, 1, At, B1); PG8_BAR; PG8_SCHED;
;             PG8_LDA(At, 0, 1); PG8_STAGE(PG8_SB(0, 0), b2, voffB0); PG8_STAGE(PG8_SB(0, 1), b2, voffB1); PG8_STAGE(PG8_SA(0, 0), a2, voffA);
;             PG8_WAIT_V(8); PG8_WAIT_L(0); PG8_BAR; PG8_MMA(1, 0, At, B0); PG8_MMA(1, 1, At, B1); PG8_BAR; PG8_SCHED;
.LBB0_173:
	s_add_u32 s40, s40, 0x40080
	s_addc_u32 s41, s41, 0
	s_add_u32 s31, s42, 0x100
	s_addc_u32 s35, s43, 0
	s_mov_b32 s71, -2
	ds_read_b128 v[128:131], v196
	ds_read_b128 v[132:135], v196 offset:1024
	ds_read_b128 v[136:139], v196 offset:2048
	ds_read_b128 v[140:143], v196 offset:3072
	ds_read_b128 v[144:147], v197
	ds_read_b128 v[148:151], v197 offset:1024
	ds_read_b128 v[186:189], v197 offset:2048
	ds_read_b128 v[202:205], v197 offset:3072
	s_add_u32 s42, s40, 0xfffc0080
	s_addc_u32 s43, s41, -1
	s_cmp_eq_u32 s71, 12
	s_cselect_b32 s45, s1, s43
	s_cselect_b32 s44, s0, s42
	s_cselect_b32 s43, s37, s35
	s_cselect_b32 s42, s36, s31
	v_lshl_add_u64 v[238:239], s[40:41], 0, v[178:179]
	s_add_i32 m0, s39, 0xc000
	ds_read_b128 v[206:209], v198
	ds_read_b128 v[210:213], v198 offset:1024
	ds_read_b128 v[214:217], v198 offset:2048
	ds_read_b128 v[218:221], v198 offset:3072
	ds_read_b128 v[222:225], v198 offset:4096
	ds_read_b128 v[226:229], v198 offset:5120
	ds_read_b128 v[230:233], v198 offset:6144
	ds_read_b128 v[234:237], v198 offset:7168
	global_load_lds_dwordx4 v[238:239], off
	v_lshl_add_u64 v[238:239], s[40:41], 0, v[180:181]
	s_add_i32 m0, s39, 0xe000
	s_nop 0
	global_load_lds_dwordx4 v[238:239], off
	s_waitcnt vmcnt(8)
	s_waitcnt lgkmcnt(0)
	s_barrier
	s_setprio 1
	s_waitcnt lgkmcnt(0)
	v_mfma_f32_16x16x32_bf16 v[124:127], v[128:131], v[206:209], 0
	v_mfma_f32_16x16x32_bf16 v[120:123], v[136:139], v[206:209], 0
	v_mfma_f32_16x16x32_bf16 v[108:111], v[128:131], v[214:217], 0
	v_mfma_f32_16x16x32_bf16 v[104:107], v[136:139], v[214:217], 0
	v_mfma_f32_16x16x32_bf16 v[92:95], v[128:131], v[222:225], 0
	v_mfma_f32_16x16x32_bf16 v[88:91], v[136:139], v[222:225], 0
	v_mfma_f32_16x16x32_bf16 v[76:79], v[128:131], v[230:233], 0
	v_mfma_f32_16x16x32_bf16 v[72:75], v[136:139], v[230:233], 0
	v_mfma_f32_16x16x32_bf16 v[124:127], v[132:135], v[210:213], v[124:127]
	v_mfma_f32_16x16x32_bf16 v[120:123], v[140:143], v[210:213], v[120:123]
	v_mfma_f32_16x16x32_bf16 v[108:111], v[132:135], v[218:221], v[108:111]
	v_mfma_f32_16x16x32_bf16 v[104:107], v[140:143], v[218:221], v[104:107]
	v_mfma_f32_16x16x32_bf16 v[92:95], v[132:135], v[226:229], v[92:95]
	v_mfma_f32_16x16x32_bf16 v[88:91], v[140:143], v[226:229], v[88:91]
	v_mfma_f32_16x16x32_bf16 v[76:79], v[132:135], v[234:237], v[76:79]
	v_mfma_f32_16x16x32_bf16 v[72:75], v[140:143], v[234:237], v[72:75]
	s_setprio 0
	s_setprio 1
	v_mfma_f32_16x16x32_bf16 v[116:119], v[144:147], v[206:209], 0
	v_mfma_f32_16x16x32_bf16 v[112:115], v[186:189], v[206:209], 0
	v_mfma_f32_16x16x32_bf16 v[100:103], v[144:147], v[214:217], 0
	v_mfma_f32_16x16x32_bf16 v[96:99], v[186:189], v[214:217], 0
	v_mfma_f32_16x16x32_bf16 v[84:87], v[144:147], v[222:225], 0
	v_mfma_f32_16x16x32_bf16 v[80:83], v[186:189], v[222:225], 0
	v_mfma_f32_16x16x32_bf16 v[68:71], v[144:147], v[230:233], 0
	v_mfma_f32_16x16x32_bf16 v[64:67], v[186:189], v[230:233], 0
	v_mfma_f32_16x16x32_bf16 v[116:119], v[148:151], v[210:213], v[116:119]
	v_mfma_f32_16x16x32_bf16 v[112:115], v[202:205], v[210:213], v[112:115]
	v_mfma_f32_16x16x32_bf16 v[100:103], v[148:151], v[218:221], v[100:103]
	v_mfma_f32_16x16x32_bf16 v[96:99], v[202:205], v[218:221], v[96:99]
	v_mfma_f32_16x16x32_bf16 v[84:87], v[148:151], v[226:229], v[84:87]
	v_mfma_f32_16x16x32_bf16 v[80:83], v[202:205], v[226:229], v[80:83]
	v_mfma_f32_16x16x32_bf16 v[68:71], v[148:151], v[234:237], v[68:71]
	v_mfma_f32_16x16x32_bf16 v[64:67], v[202:205], v[234:237], v[64:67]
	s_setprio 0
	s_barrier
	s_add_i32 s72, s59, s33
	v_lshl_add_u64 v[238:239], s[42:43], 0, v[156:157]
	s_mov_b32 m0, s72
	ds_read_b128 v[206:209], v198 offset:16384
	ds_read_b128 v[210:213], v198 offset:17408
	ds_read_b128 v[214:217], v198 offset:18432
	ds_read_b128 v[218:221], v198 offset:19456
	ds_read_b128 v[222:225], v198 offset:20480
	ds_read_b128 v[226:229], v198 offset:21504
	ds_read_b128 v[230:233], v198 offset:22528
	ds_read_b128 v[234:237], v198 offset:23552
	global_load_lds_dwordx4 v[238:239], off
	v_lshl_add_u64 v[240:241], s[42:43], 0, v[162:163]
	s_add_i32 m0, s72, 0x2000
	s_add_i32 s72, s60, s33
	global_load_lds_dwordx4 v[240:241], off
	v_lshl_add_u64 v[242:243], s[42:43], 0, v[158:159]
	s_mov_b32 m0, s72
	v_lshl_add_u64 v[244:245], s[44:45], 0, v[160:161]
	global_load_lds_dwordx4 v[242:243], off
	v_lshl_add_u64 v[242:243], s[42:43], 0, v[164:165]
	s_add_i32 m0, s72, 0x2000
	s_nop 0
	global_load_lds_dwordx4 v[242:243], off
	v_lshl_add_u64 v[242:243], s[44:45], 0, v[154:155]
	s_mov_b32 m0, s39
	s_nop 0
	global_load_lds_dwordx4 v[242:243], off
	s_mov_b32 m0, s46
	s_nop 0
	global_load_lds_dwordx4 v[244:245], off
	s_waitcnt vmcnt(8)
	s_waitcnt lgkmcnt(0)
	s_barrier
; #define PG8_STAGE(bufoff, gbase, voff) do { _Pragma("unroll") for (int _i = 0; _i < 2; ++_i) \
;         __builtin_amdgcn_global_load_lds((const unsigned*)((const char*)(gbase) + (voff)[_i]), (LAS unsigned*)(lds + (bufoff) + ldsw + _i * 8192), 16, 0, 0); } while (0)
; #define PG8_LDA(dst, b, h) do { _Pragma("unroll") for (int m = 0; m < 4; ++m) _Pragma("unroll") for (int k = 0; k < 2; ++k) dst[m][k] = *(const LAS bf16x8*)(lds + PG8_SA(b, h) + aoff + m * 2048 + k * 1024); } while (0)
; #define PG8_LDB(dst, b, h) do { _Pragma("unroll") for (int n = 0; n < 2; ++n) _Pragma("unroll") for (int k = 0; k < 2; ++k) dst[n][k] = *(const LAS bf16x8*)(lds + PG8_SB(b, h) + boff + n * 2048 + k * 1024); } while (0)
; #define PG8_MMA(ai, bj, At, Bt) do { __builtin_amdgcn_s_setprio(1); _Pragma("unroll") for (int m = 0; m < 4; ++m) _Pragma("unroll") for (int n = 0; n < 2; ++n) _Pragma("unroll") for (int k = 0; k < 2; ++k) \
;         acc[ai][bj][m][n] = __builtin_amdgcn_mfma_f32_16x16x32_bf16(Bt[n][k], At[m][k], acc[ai][bj][m][n], 0, 0, 0); __builtin_amdgcn_s_setprio(0); } while (0)
; #define PG8_WAIT_V(n) asm volatile("s_waitcnt vmcnt(" #n ")" ::: "memory")
; #define PG8_WAIT_L(n) asm volatile("s_waitcnt lgkmcnt(" #n ")" ::: "memory")
; #define PG8_BAR __builtin_amdgcn_s_barrier()
; #define PG8_SCHED __builtin_amdgcn_sched_barrier(0)
; template <class Epi, class Sched>
; __device__ __forceinline__ void gemm_phase(LAS unsigned char* lds, const Sched& S, const Epi& E, bool natural = false) {
;     ...
;             PG8_WAIT_V(8); PG8_WAIT_L(0); PG8_BAR; PG8_MMA(1, 0, At, B0); PG8_MMA(1, 1, At, B1); PG8_BAR; PG8_SCHED;
;             PG8_LDB(B0, 1, 0); PG8_LDB(B1, 1, 1); PG8_SCHED; PG8_LDA(At, 1, 0); PG8_STAGE(PG8_SA(0, 1), a2 + hstep, voffA);
;             PG8_WAIT_V(8); PG8_WAIT_L(0); PG8_BAR; PG8_MMA(0, 0, At, B0); PG8_MMA(0, 1, At, B1); PG8_BAR; PG8_SCHED;
;             PG8_LDA(At, 1, 1); PG8_STAGE(PG8_SB(1, 0), b3, voffB0); PG8_STAGE(PG8_SB(1, 1), b3, voffB1); PG8_STAGE(PG8_SA(1, 0), a3, voffA);
	s_setprio 1
	s_waitcnt lgkmcnt(0)
	v_mfma_f32_16x16x32_bf16 v[60:63], v[128:131], v[206:209], 0
	v_mfma_f32_16x16x32_bf16 v[56:59], v[136:139], v[206:209], 0
	v_mfma_f32_16x16x32_bf16 v[44:47], v[128:131], v[214:217], 0
	v_mfma_f32_16x16x32_bf16 v[40:43], v[136:139], v[214:217], 0
	v_mfma_f32_16x16x32_bf16 v[28:31], v[128:131], v[222:225], 0
	v_mfma_f32_16x16x32_bf16 v[24:27], v[136:139], v[222:225], 0
	v_mfma_f32_16x16x32_bf16 v[12:15], v[128:131], v[230:233], 0
	v_mfma_f32_16x16x32_bf16 v[8:11], v[136:139], v[230:233], 0
	v_mfma_f32_16x16x32_bf16 v[60:63], v[132:135], v[210:213], v[60:63]
	v_mfma_f32_16x16x32_bf16 v[56:59], v[140:143], v[210:213], v[56:59]
	v_mfma_f32_16x16x32_bf16 v[44:47], v[132:135], v[218:221], v[44:47]
	v_mfma_f32_16x16x32_bf16 v[40:43], v[140:143], v[218:221], v[40:43]
	v_mfma_f32_16x16x32_bf16 v[28:31], v[132:135], v[226:229], v[28:31]
	v_mfma_f32_16x16x32_bf16 v[24:27], v[140:143], v[226:229], v[24:27]
	v_mfma_f32_16x16x32_bf16 v[12:15], v[132:135], v[234:237], v[12:15]
	v_mfma_f32_16x16x32_bf16 v[8:11], v[140:143], v[234:237], v[8:11]
	s_setprio 0
	s_setprio 1
	v_mfma_f32_16x16x32_bf16 v[52:55], v[144:147], v[206:209], 0
	v_mfma_f32_16x16x32_bf16 v[48:51], v[186:189], v[206:209], 0
	v_mfma_f32_16x16x32_bf16 v[36:39], v[144:147], v[214:217], 0
	v_mfma_f32_16x16x32_bf16 v[32:35], v[186:189], v[214:217], 0
	v_mfma_f32_16x16x32_bf16 v[20:23], v[144:147], v[222:225], 0
	v_mfma_f32_16x16x32_bf16 v[16:19], v[186:189], v[222:225], 0
	v_mfma_f32_16x16x32_bf16 v[4:7], v[144:147], v[230:233], 0
	v_mfma_f32_16x16x32_bf16 v[0:3], v[186:189], v[230:233], 0
	v_mfma_f32_16x16x32_bf16 v[52:55], v[148:151], v[210:213], v[52:55]
	v_mfma_f32_16x16x32_bf16 v[48:51], v[202:205], v[210:213], v[48:51]
	v_mfma_f32_16x16x32_bf16 v[36:39], v[148:151], v[218:221], v[36:39]
	v_mfma_f32_16x16x32_bf16 v[32:35], v[202:205], v[218:221], v[32:35]
	v_mfma_f32_16x16x32_bf16 v[20:23], v[148:151], v[226:229], v[20:23]
	v_mfma_f32_16x16x32_bf16 v[16:19], v[202:205], v[226:229], v[16:19]
	v_mfma_f32_16x16x32_bf16 v[4:7], v[148:151], v[234:237], v[4:7]
	v_mfma_f32_16x16x32_bf16 v[0:3], v[202:205], v[234:237], v[0:3]
	s_setprio 0
	s_barrier
	s_add_i32 s72, 0, 0x18000
	s_add_i32 s73, 0, 0x1c000
	v_add_u32_e32 v140, s72, v192
	v_add_u32_e32 v166, s73, v192
	ds_read_b128 v[128:131], v140
	ds_read_b128 v[132:135], v140 offset:1024
	ds_read_b128 v[136:139], v140 offset:2048
	ds_read_b128 v[140:143], v140 offset:3072
	ds_read_b128 v[144:147], v166
	ds_read_b128 v[148:151], v166 offset:1024
	ds_read_b128 v[186:189], v166 offset:2048
	ds_read_b128 v[202:205], v166 offset:3072
	s_add_u32 s44, s44, 0x40000
	s_addc_u32 s45, s45, 0
	s_mov_b32 m0, s47
	v_lshl_add_u64 v[246:247], s[44:45], 0, v[154:155]
	ds_read_b128 v[206:209], v198 offset:32768
	ds_read_b128 v[210:213], v198 offset:33792
	ds_read_b128 v[214:217], v198 offset:34816
	ds_read_b128 v[218:221], v198 offset:35840
	ds_read_b128 v[222:225], v198 offset:36864
	ds_read_b128 v[226:229], v198 offset:37888
	ds_read_b128 v[230:233], v198 offset:38912
	ds_read_b128 v[234:237], v198 offset:39936
	global_load_lds_dwordx4 v[246:247], off
	v_lshl_add_u64 v[246:247], s[44:45], 0, v[160:161]
	s_mov_b32 m0, s49
	s_nop 0
	global_load_lds_dwordx4 v[246:247], off
	s_waitcnt vmcnt(8)
	s_waitcnt lgkmcnt(0)
	s_barrier
	s_setprio 1
	s_waitcnt lgkmcnt(0)
	v_mfma_f32_16x16x32_bf16 v[124:127], v[128:131], v[206:209], v[124:127]
	v_mfma_f32_16x16x32_bf16 v[120:123], v[136:139], v[206:209], v[120:123]
	v_mfma_f32_16x16x32_bf16 v[108:111], v[128:131], v[214:217], v[108:111]
	v_mfma_f32_16x16x32_bf16 v[104:107], v[136:139], v[214:217], v[104:107]
	v_mfma_f32_16x16x32_bf16 v[92:95], v[128:131], v[222:225], v[92:95]
	v_mfma_f32_16x16x32_bf16 v[88:91], v[136:139], v[222:225], v[88:91]
	v_mfma_f32_16x16x32_bf16 v[76:79], v[128:131], v[230:233], v[76:79]
	v_mfma_f32_16x16x32_bf16 v[72:75], v[136:139], v[230:233], v[72:75]
	v_mfma_f32_16x16x32_bf16 v[124:127], v[132:135], v[210:213], v[124:127]
	v_mfma_f32_16x16x32_bf16 v[120:123], v[140:143], v[210:213], v[120:123]
	v_mfma_f32_16x16x32_bf16 v[108:111], v[132:135], v[218:221], v[108:111]
	v_mfma_f32_16x16x32_bf16 v[104:107], v[140:143], v[218:221], v[104:107]
	v_mfma_f32_16x16x32_bf16 v[92:95], v[132:135], v[226:229], v[92:95]
	v_mfma_f32_16x16x32_bf16 v[88:91], v[140:143], v[226:229], v[88:91]
	v_mfma_f32_16x16x32_bf16 v[76:79], v[132:135], v[234:237], v[76:79]
	v_mfma_f32_16x16x32_bf16 v[72:75], v[140:143], v[234:237], v[72:75]
	s_setprio 0
	s_setprio 1
	v_mfma_f32_16x16x32_bf16 v[116:119], v[144:147], v[206:209], v[116:119]
	v_mfma_f32_16x16x32_bf16 v[112:115], v[186:189], v[206:209], v[112:115]
	v_mfma_f32_16x16x32_bf16 v[100:103], v[144:147], v[214:217], v[100:103]
	v_mfma_f32_16x16x32_bf16 v[96:99], v[186:189], v[214:217], v[96:99]
	v_mfma_f32_16x16x32_bf16 v[84:87], v[144:147], v[222:225], v[84:87]
	v_mfma_f32_16x16x32_bf16 v[80:83], v[186:189], v[222:225], v[80:83]
	v_mfma_f32_16x16x32_bf16 v[68:71], v[144:147], v[230:233], v[68:71]
	v_mfma_f32_16x16x32_bf16 v[64:67], v[186:189], v[230:233], v[64:67]
	v_mfma_f32_16x16x32_bf16 v[116:119], v[148:151], v[210:213], v[116:119]
	v_mfma_f32_16x16x32_bf16 v[112:115], v[202:205], v[210:213], v[112:115]
	v_mfma_f32_16x16x32_bf16 v[100:103], v[148:151], v[218:221], v[100:103]
	v_mfma_f32_16x16x32_bf16 v[96:99], v[202:205], v[218:221], v[96:99]
	v_mfma_f32_16x16x32_bf16 v[84:87], v[148:151], v[226:229], v[84:87]
	v_mfma_f32_16x16x32_bf16 v[80:83], v[202:205], v[226:229], v[80:83]
	v_mfma_f32_16x16x32_bf16 v[68:71], v[148:151], v[234:237], v[68:71]
	v_mfma_f32_16x16x32_bf16 v[64:67], v[202:205], v[234:237], v[64:67]
	s_setprio 0
	s_barrier
; #define PG8_STAGE(bufoff, gbase, voff) do { _Pragma("unroll") for (int _i = 0; _i < 2; ++_i) \
;         __builtin_amdgcn_global_load_lds((const unsigned*)((const char*)(gbase) + (voff)[_i]), (LAS unsigned*)(lds + (bufoff) + ldsw + _i * 8192), 16, 0, 0); } while (0)
; #define PG8_LDA(dst, b, h) do { _Pragma("unroll") for (int m = 0; m < 4; ++m) _Pragma("unroll") for (int k = 0; k < 2; ++k) dst[m][k] = *(const LAS bf16x8*)(lds + PG8_SA(b, h) + aoff + m * 2048 + k * 1024); } while (0)
; #define PG8_MMA(ai, bj, At, Bt) do { __builtin_amdgcn_s_setprio(1); _Pragma("unroll") for (int m = 0; m < 4; ++m) _Pragma("unroll") for (int n = 0; n < 2; ++n) _Pragma("unroll") for (int k = 0; k < 2; ++k) \
;         acc[ai][bj][m][n] = __builtin_amdgcn_mfma_f32_16x16x32_bf16(Bt[n][k], At[m][k], acc[ai][bj][m][n], 0, 0, 0); __builtin_amdgcn_s_setprio(0); } while (0)
; #define PG8_WAIT_V(n) asm volatile("s_waitcnt vmcnt(" #n ")" ::: "memory")
; #define PG8_WAIT_L(n) asm volatile("s_waitcnt lgkmcnt(" #n ")" ::: "memory")
; #define PG8_BAR __builtin_amdgcn_s_barrier()
; #define PG8_SCHED __builtin_amdgcn_sched_barrier(0)
; template <class Epi, class Sched>
; __device__ __forceinline__ void gemm_phase(LAS unsigned char* lds, const Sched& S, const Epi& E, bool natural = false) {
;     ...
;             PG8_LDA(At, 1, 1); PG8_STAGE(PG8_SB(1, 0), b3, voffB0); PG8_STAGE(PG8_SB(1, 1), b3, voffB1); PG8_STAGE(PG8_SA(1, 0), a3, voffA);
;             PG8_WAIT_V(8); PG8_WAIT_L(0); PG8_BAR; PG8_MMA(1, 0, At, B0); PG8_MMA(1, 1, At, B1); PG8_BAR; PG8_SCHED;
;         }
	s_add_u32 s42, s42, 0x80
	s_addc_u32 s43, s43, 0
	s_add_i32 s44, s72, s33
	v_lshl_add_u64 v[238:239], v[238:239], 0, s[12:13]
	s_mov_b32 m0, s44
	ds_read_b128 v[206:209], v198 offset:49152
	ds_read_b128 v[210:213], v198 offset:50176
	ds_read_b128 v[214:217], v198 offset:51200
	ds_read_b128 v[218:221], v198 offset:52224
	ds_read_b128 v[222:225], v198 offset:53248
	ds_read_b128 v[226:229], v198 offset:54272
	ds_read_b128 v[230:233], v198 offset:55296
	ds_read_b128 v[234:237], v198 offset:56320
	global_load_lds_dwordx4 v[238:239], off
	v_lshl_add_u64 v[238:239], v[240:241], 0, s[12:13]
	s_add_i32 m0, s44, 0x2000
	s_add_i32 s44, s73, s33
	global_load_lds_dwordx4 v[238:239], off
	v_lshl_add_u64 v[238:239], s[42:43], 0, v[158:159]
	s_mov_b32 m0, s44
	s_nop 0
	global_load_lds_dwordx4 v[238:239], off
	v_lshl_add_u64 v[238:239], s[42:43], 0, v[164:165]
	s_add_i32 m0, s44, 0x2000
	s_nop 0
	global_load_lds_dwordx4 v[238:239], off
	v_lshl_add_u64 v[238:239], v[242:243], 0, s[12:13]
	s_mov_b32 m0, s51
	s_nop 0
	global_load_lds_dwordx4 v[238:239], off
	v_lshl_add_u64 v[238:239], v[244:245], 0, s[12:13]
	s_mov_b32 m0, s52
	s_nop 0
	global_load_lds_dwordx4 v[238:239], off
	s_waitcnt vmcnt(8)
	s_waitcnt lgkmcnt(0)
	s_barrier
	s_setprio 1
	s_waitcnt lgkmcnt(0)
	v_mfma_f32_16x16x32_bf16 v[60:63], v[128:131], v[206:209], v[60:63]
	v_mfma_f32_16x16x32_bf16 v[56:59], v[136:139], v[206:209], v[56:59]
	v_mfma_f32_16x16x32_bf16 v[44:47], v[128:131], v[214:217], v[44:47]
	v_mfma_f32_16x16x32_bf16 v[40:43], v[136:139], v[214:217], v[40:43]
	v_mfma_f32_16x16x32_bf16 v[28:31], v[128:131], v[222:225], v[28:31]
	v_mfma_f32_16x16x32_bf16 v[24:27], v[136:139], v[222:225], v[24:27]
	v_mfma_f32_16x16x32_bf16 v[12:15], v[128:131], v[230:233], v[12:15]
	v_mfma_f32_16x16x32_bf16 v[8:11], v[136:139], v[230:233], v[8:11]
	v_mfma_f32_16x16x32_bf16 v[60:63], v[132:135], v[210:213], v[60:63]
	v_mfma_f32_16x16x32_bf16 v[56:59], v[140:143], v[210:213], v[56:59]
	v_mfma_f32_16x16x32_bf16 v[44:47], v[132:135], v[218:221], v[44:47]
	v_mfma_f32_16x16x32_bf16 v[40:43], v[140:143], v[218:221], v[40:43]
	v_mfma_f32_16x16x32_bf16 v[28:31], v[132:135], v[226:229], v[28:31]
	v_mfma_f32_16x16x32_bf16 v[24:27], v[140:143], v[226:229], v[24:27]
	v_mfma_f32_16x16x32_bf16 v[12:15], v[132:135], v[234:237], v[12:15]
	v_mfma_f32_16x16x32_bf16 v[8:11], v[140:143], v[234:237], v[8:11]
	s_setprio 0
	s_setprio 1
	v_mfma_f32_16x16x32_bf16 v[52:55], v[144:147], v[206:209], v[52:55]
	v_mfma_f32_16x16x32_bf16 v[48:51], v[186:189], v[206:209], v[48:51]
	v_mfma_f32_16x16x32_bf16 v[36:39], v[144:147], v[214:217], v[36:39]
	v_mfma_f32_16x16x32_bf16 v[32:35], v[186:189], v[214:217], v[32:35]
	v_mfma_f32_16x16x32_bf16 v[20:23], v[144:147], v[222:225], v[20:23]
	v_mfma_f32_16x16x32_bf16 v[16:19], v[186:189], v[222:225], v[16:19]
	v_mfma_f32_16x16x32_bf16 v[4:7], v[144:147], v[230:233], v[4:7]
	v_mfma_f32_16x16x32_bf16 v[0:3], v[186:189], v[230:233], v[0:3]
	v_mfma_f32_16x16x32_bf16 v[52:55], v[148:151], v[210:213], v[52:55]
	v_mfma_f32_16x16x32_bf16 v[48:51], v[202:205], v[210:213], v[48:51]
	v_mfma_f32_16x16x32_bf16 v[36:39], v[148:151], v[218:221], v[36:39]
	v_mfma_f32_16x16x32_bf16 v[32:35], v[202:205], v[218:221], v[32:35]
	v_mfma_f32_16x16x32_bf16 v[20:23], v[148:151], v[226:229], v[20:23]
	v_mfma_f32_16x16x32_bf16 v[16:19], v[202:205], v[226:229], v[16:19]
	v_mfma_f32_16x16x32_bf16 v[4:7], v[148:151], v[234:237], v[4:7]
	v_mfma_f32_16x16x32_bf16 v[0:3], v[202:205], v[234:237], v[0:3]
	s_setprio 0
	s_barrier
	s_add_i32 s71, s71, 2
	s_add_u32 s40, s40, 0x100
	s_addc_u32 s41, s41, 0
	s_add_u32 s31, s31, 0x100
	s_addc_u32 s35, s35, 0
	s_cmp_gt_u32 s71, 13
	s_cbranch_scc0 .LBB0_174
